# attention fast path: s_setprio 2 over the K-fragment reads and QK MFMAs, back to 0 for the softmax/PV part
# speedup vs baseline: 1.0034x; 1.0034x over previous
; DI void attn_item(const Params& p, int l, int item, char* lds) {
;     ...
;     for (int kt = 0; kt < 2; ++kt) {
; #pragma unroll
;       for (int e = 0; e < 16; ++e) s[kt][e] = 0.f;
; #pragma unroll
;       for (int ks = 0; ks < 4; ++ks) {
;         const bf16x8 kf = *(const bf16x8*)(Ks + (m * 64 + kt * 32 + q) * ALD + ks * 16 + hh * 8);
;         s[kt] = __builtin_amdgcn_mfma_f32_32x32x16_bf16(kf, qf[ks], s[kt], 0, 0, 0);
;       }
;     }
;     float mx = -1e30f;
;     const float dbase = qposf - (float)(j * 64 + 4 * hh);
; #pragma unroll
;     for (int kt = 0; kt < 2; ++kt)
; #pragma unroll
;       for (int e = 0; e < 16; ++e) {
;         const float dd = dbase - (float)(kt * 32 + (e & 3) + 8 * (e >> 2));
;         const float v = s[kt][e] * c1 - sl2 * fabsf(dd);
;         s[kt][e] = v; mx = fmaxf(mx, v);
;       }
;     mx = fmaxf(mx, __shfl_xor(mx, 32));
;     const float mnew = fmaxf(mrun, mx);
;     const float alpha = __builtin_amdgcn_exp2f(mrun - mnew);
;     const bool resc = mnew > mrun;
;     mrun = mnew;
;     float ps = 0.f;
; #pragma unroll
;     for (int kt = 0; kt < 2; ++kt)
; #pragma unroll
;       for (int e = 0; e < 16; ++e) { const float pe = __builtin_amdgcn_exp2f(s[kt][e] - mnew); s[kt][e] = pe; ps += pe; }
;     lrun = lrun * alpha + ps;
;     if (__any(resc)) {
; #pragma unroll
;       for (int i = 0; i < 4; ++i)
; #pragma unroll
;         for (int e = 0; e < 16; ++e) O[i][e] *= alpha;
.Lfa_body:
	s_setprio 2
	ds_read_b128 v[2:5], v202
	ds_read_b128 v[6:9], v202 offset:32
	ds_read_b128 v[10:13], v202 offset:64
	ds_read_b128 v[222:225], v202 offset:96
	ds_read_b128 v[226:229], v202 offset:4608
	v_mfma_f32_32x32x8_bf16 v[96:111], v[206:207], v[214:215], 0
	v_mfma_f32_32x32x8_bf16 v[80:95], v[206:207], v[216:217], 0
	s_waitcnt lgkmcnt(4)
	v_mfma_f32_32x32x16_bf16 v[96:111], v[2:5], v[120:123], v[96:111]
	ds_read_b128 v[2:5], v202 offset:4640
	s_waitcnt lgkmcnt(4)
	v_mfma_f32_32x32x16_bf16 v[96:111], v[6:9], v[112:115], v[96:111]
	ds_read_b128 v[6:9], v202 offset:4672
	s_waitcnt lgkmcnt(4)
	v_mfma_f32_32x32x16_bf16 v[96:111], v[10:13], v[116:119], v[96:111]
	ds_read_b128 v[10:13], v202 offset:4704
	s_waitcnt lgkmcnt(4)
	v_mfma_f32_32x32x16_bf16 v[96:111], v[222:225], v[124:127], v[96:111]
	s_waitcnt lgkmcnt(3)
	v_mfma_f32_32x32x16_bf16 v[80:95], v[226:229], v[120:123], v[80:95]
	s_waitcnt lgkmcnt(2)
	v_mfma_f32_32x32x16_bf16 v[80:95], v[2:5], v[112:115], v[80:95]
	s_waitcnt lgkmcnt(1)
	v_mfma_f32_32x32x16_bf16 v[80:95], v[6:9], v[116:119], v[80:95]
	s_waitcnt lgkmcnt(0)
	v_mfma_f32_32x32x16_bf16 v[80:95], v[10:13], v[124:127], v[80:95]
	s_setprio 0
	v_add_u32_e32 v161, 0x4800, v201
	v_add_u32_e32 v173, 0x5800, v201
	v_add_u32_e32 v188, 0x6800, v201
	v_add_u32_e32 v208, 0x7800, v201
	ds_read2_b64 v[222:225], v208 offset0:192 offset1:194
	ds_read2_b64 v[226:229], v161 offset0:4 offset1:6
	s_lshl_b32 s2, s93, 6
	s_sub_i32 s2, s2, 64
	v_cvt_f32_u32_e32 v14, s2
	v_sub_f32_e32 v14, v187, v14
	v_mul_f32_e32 v14, v189, v14
	ds_read2_b64 v[2:5], v161 offset1:2
	ds_read2_b64 v[6:9], v173 offset0:64 offset1:66
	ds_read2_b64 v[10:13], v188 offset0:128 offset1:130
	v_max3_f32 v0, v96, v97, v98
	v_max3_f32 v15, v80, v81, v82
	v_max3_f32 v0, v0, v99, v100
	v_max3_f32 v15, v15, v83, v84
	v_max3_f32 v0, v0, v101, v102
	v_max3_f32 v15, v15, v85, v86
	v_max3_f32 v0, v0, v103, v104
	v_max3_f32 v15, v15, v87, v88
	v_max3_f32 v0, v0, v105, v106
	v_max3_f32 v15, v15, v89, v90
	v_max3_f32 v0, v0, v107, v108
	v_max3_f32 v15, v15, v91, v92
	v_max3_f32 v0, v0, v109, v110
	v_max3_f32 v15, v15, v93, v94
	v_max_f32_e32 v0, v0, v111
	v_max_f32_e32 v15, v15, v95
	v_max_f32_e32 v0, v0, v15
	v_mov_b32_e32 v15, v0
	s_nop 1
	v_permlane32_swap_b32_e32 v15, v0
	s_nop 1
	v_max_f32_e32 v0, v0, v15
	v_fma_f32 v0, v0, s35, -v14
	v_sub_f32_e32 v15, v0, v204
	v_cmp_lt_f32_e32 vcc, 0x41000000, v15
	s_nop 1
	v_cndmask_b32_e32 v15, v204, v0, vcc
	v_sub_f32_e32 v0, v204, v15
	v_exp_f32_e32 v0, v0
	v_mov_b32_e32 v204, v15
	v_add_f32_e32 v14, v15, v14
	s_cbranch_vccz .Lfa_keep
	v_pk_mul_f32 v[78:79], v[78:79], v[0:1] op_sel_hi:[1,0]
	v_pk_mul_f32 v[76:77], v[76:77], v[0:1] op_sel_hi:[1,0]
	v_pk_mul_f32 v[74:75], v[74:75], v[0:1] op_sel_hi:[1,0]
	v_pk_mul_f32 v[72:73], v[72:73], v[0:1] op_sel_hi:[1,0]
	v_pk_mul_f32 v[70:71], v[70:71], v[0:1] op_sel_hi:[1,0]
	v_pk_mul_f32 v[68:69], v[68:69], v[0:1] op_sel_hi:[1,0]
	v_pk_mul_f32 v[66:67], v[66:67], v[0:1] op_sel_hi:[1,0]
	v_pk_mul_f32 v[64:65], v[64:65], v[0:1] op_sel_hi:[1,0]
	v_pk_mul_f32 v[62:63], v[62:63], v[0:1] op_sel_hi:[1,0]
	v_pk_mul_f32 v[60:61], v[60:61], v[0:1] op_sel_hi:[1,0]
	v_pk_mul_f32 v[58:59], v[58:59], v[0:1] op_sel_hi:[1,0]
	v_pk_mul_f32 v[56:57], v[56:57], v[0:1] op_sel_hi:[1,0]
	v_pk_mul_f32 v[54:55], v[54:55], v[0:1] op_sel_hi:[1,0]
	v_pk_mul_f32 v[52:53], v[52:53], v[0:1] op_sel_hi:[1,0]
	v_pk_mul_f32 v[50:51], v[50:51], v[0:1] op_sel_hi:[1,0]
	v_pk_mul_f32 v[48:49], v[48:49], v[0:1] op_sel_hi:[1,0]
	v_pk_mul_f32 v[46:47], v[46:47], v[0:1] op_sel_hi:[1,0]
	v_pk_mul_f32 v[44:45], v[44:45], v[0:1] op_sel_hi:[1,0]
	v_pk_mul_f32 v[42:43], v[42:43], v[0:1] op_sel_hi:[1,0]
	v_pk_mul_f32 v[40:41], v[40:41], v[0:1] op_sel_hi:[1,0]
	v_pk_mul_f32 v[38:39], v[38:39], v[0:1] op_sel_hi:[1,0]
	v_pk_mul_f32 v[36:37], v[36:37], v[0:1] op_sel_hi:[1,0]
	v_pk_mul_f32 v[34:35], v[34:35], v[0:1] op_sel_hi:[1,0]
	v_pk_mul_f32 v[32:33], v[32:33], v[0:1] op_sel_hi:[1,0]
	v_pk_mul_f32 v[30:31], v[30:31], v[0:1] op_sel_hi:[1,0]
	v_pk_mul_f32 v[28:29], v[28:29], v[0:1] op_sel_hi:[1,0]
	v_pk_mul_f32 v[26:27], v[26:27], v[0:1] op_sel_hi:[1,0]
	v_pk_mul_f32 v[24:25], v[24:25], v[0:1] op_sel_hi:[1,0]
	v_pk_mul_f32 v[22:23], v[22:23], v[0:1] op_sel_hi:[1,0]
	v_pk_mul_f32 v[20:21], v[20:21], v[0:1] op_sel_hi:[1,0]
	v_pk_mul_f32 v[18:19], v[18:19], v[0:1] op_sel_hi:[1,0]
	v_pk_mul_f32 v[16:17], v[16:17], v[0:1] op_sel_hi:[1,0]
